# v44: v41 + the six dead V-tile preloads of the compiled attention loop removed from the unit setup
# speedup vs baseline: 1.0076x; 1.0035x over previous
.LBB0_232:
	v_mov_b32_e32 v3, v195
	v_mov_b32_e32 v5, v193
	v_ashrrev_i32_e32 v0, 4, v3
	v_ashrrev_i32_e32 v1, 31, v0
	v_lshl_add_u64 v[6:7], s[46:47], 0, v[0:1]
	v_lshlrev_b32_e32 v2, 4, v3
	v_lshlrev_b64 v[6:7], 12, v[6:7]
	v_and_b32_e32 v4, 0xf0, v2
	v_lshl_add_u64 v[6:7], s[74:75], 0, v[6:7]
	v_lshl_add_u64 v[6:7], v[6:7], 0, v[4:5]
	v_add_co_u32_e32 v8, vcc, s35, v6
	s_xor_b64 s[2:3], s[6:7], -1
	s_nop 0
	v_addc_co_u32_e32 v9, vcc, 0, v7, vcc
	v_add_co_u32_e32 v8, vcc, s73, v6
	s_lshl_b64 s[8:9], s[8:9], 4
	s_nop 0
	v_addc_co_u32_e32 v9, vcc, 0, v7, vcc
	v_add_co_u32_e32 v10, vcc, s20, v6
	s_add_u32 s8, s45, s8
	s_nop 0
	v_addc_co_u32_e32 v11, vcc, 0, v7, vcc
	v_add_co_u32_e32 v8, vcc, s21, v6
	s_addc_u32 s9, s72, s9
	s_nop 0
	v_addc_co_u32_e32 v9, vcc, 0, v7, vcc
	v_add_co_u32_e32 v6, vcc, s22, v6
	s_and_b64 s[6:7], s[6:7], exec
	s_nop 0
	v_addc_co_u32_e32 v7, vcc, 0, v7, vcc
	v_readfirstlane_b32 s6, v3
	s_cselect_b32 s5, s28, s82
	v_and_b32_e32 v5, 31, v3
	s_ashr_i32 s81, s6, 7
	s_ashr_i32 s6, s6, 1
	s_andn2_b32 s6, s6, 31
	v_lshl_or_b32 v6, s5, 8, v5
	s_ashr_i32 s7, s6, 31
	v_or_b32_e32 v6, s46, v6
	v_mov_b32_e32 v7, s47
	v_ashrrev_i32_e32 v10, 3, v3
	v_bfe_u32 v11, v3, 5, 1
	v_lshl_add_u64 v[6:7], v[6:7], 0, s[6:7]
	v_mul_lo_u32 v13, v10, s29
	v_and_b32_e32 v12, 0x70, v2
	s_movk_i32 s6, 0x140
	v_add3_u32 v196, 0, v13, v12
	v_mul_lo_u32 v13, v0, s6
	v_mul_u32_u24_e32 v5, 0x90, v5
	v_lshlrev_b32_e32 v14, 4, v11
	v_add3_u32 v198, 0, v13, v4
	v_add3_u32 v200, 0, v5, v14
	v_bfe_u32 v5, v3, 2, 2
	v_and_b32_e32 v13, 16, v3
	v_lshlrev_b32_e32 v3, 2, v3
	v_lshl_or_b32 v5, v11, 2, v5
	v_and_or_b32 v3, v3, 12, v13
	v_mul_u32_u24_e32 v5, 0x140, v5
	v_lshlrev_b32_e32 v3, 1, v3
	v_cmp_lt_i32_e32 vcc, v210, v204
	s_lshl_b32 s10, s5, 2
	v_add3_u32 v201, 0, v5, v3
	v_cndmask_b32_e32 v3, v202, v210, vcc
	s_add_i32 s81, s81, s10
	v_lshlrev_b64 v[8:9], 12, v[6:7]
	v_lshlrev_b32_e32 v214, 2, v3
	v_ashrrev_i32_e32 v3, 31, v2
	v_lshl_add_u64 v[8:9], s[74:75], 0, v[8:9]
	v_lshlrev_b32_e32 v192, 3, v11
	v_mov_b32_e32 v15, v193
	v_ashrrev_i32_e32 v11, 31, v10
	v_lshl_add_u64 v[170:171], v[2:3], 4, s[8:9]
	v_lshlrev_b64 v[2:3], 11, v[6:7]
	s_cmp_gt_i32 s81, -1
	v_lshl_add_u64 v[166:167], v[8:9], 0, v[14:15]
	v_lshl_add_u64 v[8:9], s[46:47], 0, v[10:11]
	v_lshl_add_u64 v[2:3], s[76:77], 0, v[2:3]
	s_cselect_b64 s[64:65], -1, 0
	s_or_b32 s6, s10, 1
	v_lshlrev_b64 v[8:9], 12, v[8:9]
	v_lshl_add_u64 v[174:175], v[2:3], 0, v[192:193]
	s_cmp_lt_i32 s6, s81
	v_lshlrev_b64 v[2:3], 12, v[10:11]
	v_lshlrev_b64 v[0:1], 12, v[0:1]
	v_lshl_add_u64 v[8:9], s[74:75], 0, v[8:9]
	v_mov_b32_e32 v13, v193
	s_cselect_b64 s[66:67], -1, 0
	s_lshl_b32 s5, s5, 20
	v_or_b32_e32 v2, v2, v12
	v_or_b32_e32 v0, v0, v4
	v_lshl_add_u64 v[168:169], v[8:9], 0, v[12:13]
	v_lshl_add_u64 v[172:173], s[38:39], 0, v[14:15]
	s_or_b32 s27, s5, 0x40000
	v_lshl_add_u64 v[176:177], s[78:79], 0, v[2:3]
	v_lshl_add_u64 v[178:179], s[30:31], 0, v[0:1]
	s_mov_b64 s[84:85], -1
	s_mov_b64 s[68:69], 0
	s_branch .LBB0_234
